# G14 epilogue: B-tile row remap + DPP half-row swap so each store writes 8 rows x 128B full lines
# speedup vs baseline: 1.0051x; 1.0051x over previous
.LBB0_1557:
	s_or_b64 exec, exec, s[0:1]
	v_readlane_b32 s0, v247, 14
	v_mov_b32_e32 v8, v202
	v_readlane_b32 s1, v247, 15
	s_waitcnt lgkmcnt(0)
	s_barrier
	s_and_b64 vcc, exec, s[0:1]
	v_readfirstlane_b32 s28, v8
	s_cbranch_vccz .LBB0_1569
	v_lshlrev_b32_e32 v0, 4, v8
	s_add_u32 s29, s58, 0xa100000
	v_readlane_b32 s1, v247, 8
	v_add_u32_e32 v1, 0x2000, v0
	s_addc_u32 s30, s59, 0
	s_lshr_b32 s1, s1, 29
	v_readlane_b32 s4, v248, 45
	v_ashrrev_i32_e32 v2, 31, v1
	s_add_i32 s1, s4, s1
	v_lshrrev_b32_e32 v2, 22, v2
	s_ashr_i32 s0, s28, 6
	s_and_b32 s2, s1, -8
	v_add_u32_e32 v2, v1, v2
	s_ashr_i32 s3, s28, 8
	s_lshl_b32 s31, s0, 10
	s_sub_i32 s2, s4, s2
	v_ashrrev_i32_e32 v9, 10, v2
	s_cmp_lt_i32 s2, 0
	s_movk_i32 s34, 0x91
	v_mul_i32_i24_e32 v2, 0x400, v9
	s_cselect_b32 s4, s34, 0x90
	v_sub_u32_e32 v1, v1, v2
	s_mul_i32 s2, s4, s2
	s_ashr_i32 s1, s1, 3
	v_lshrrev_b32_e32 v2, 4, v1
	s_add_i32 s1, s2, s1
	v_bitop3_b32 v1, v2, v1, 32 bitop3:0x6c
	s_ashr_i32 s2, s1, 31
	v_ashrrev_i32_e32 v2, 31, v1
	s_lshr_b32 s2, s2, 24
	v_lshrrev_b32_e32 v2, 26, v2
	s_add_i32 s2, s1, s2
	v_add_u32_e32 v2, v1, v2
	v_lshlrev_b32_e32 v3, 3, v9
	s_ashr_i32 s2, s2, 8
	v_ashrrev_i32_e32 v10, 6, v2
	v_and_b32_e32 v3, -16, v3
	s_lshl_b32 s6, s2, 3
	s_lshl_b32 s2, s2, 8
	v_add_u32_e32 v3, v10, v3
	s_sub_i32 s1, s1, s2
	v_and_b32_e32 v4, 3, v10
	s_mov_b32 s2, 0xfffe0
	v_lshrrev_b32_e32 v5, 2, v3
	v_lshlrev_b32_e32 v6, 1, v3
	v_and_b32_e32 v2, 0xc0, v2
	v_and_or_b32 v4, v3, s2, v4
	v_and_b32_e32 v5, 4, v5
	v_and_b32_e32 v6, 24, v6
	v_sub_u32_e32 v1, v1, v2
	v_mov_b32_e32 v2, 1
	v_or3_b32 v4, v4, v5, v6
	v_lshlrev_b32_e32 v5, 5, v9
	v_ashrrev_i16_sdwa v1, v2, sext(v1) dst_sel:DWORD dst_unused:UNUSED_PAD src0_sel:DWORD src1_sel:BYTE_0
	v_and_b32_e32 v5, 32, v5
	v_bfe_i32 v11, v1, 0, 16
	v_add_lshl_u32 v1, v5, v11, 1
	v_lshl_add_u32 v128, v4, 12, v1
	v_lshl_add_u32 v130, v3, 12, v1
	v_bfe_i32 v1, v8, 27, 1
	v_lshrrev_b32_e32 v1, 22, v1
	v_add_u32_e32 v1, v0, v1
	v_and_b32_e32 v1, 0xfffffc00, v1
	v_sub_u32_e32 v0, v0, v1
	v_lshrrev_b32_e32 v1, 4, v0
	v_ashrrev_i32_e32 v3, 31, v8
	v_bitop3_b32 v0, v1, v0, 32 bitop3:0x6c
	v_lshrrev_b32_e32 v3, 26, v3
	v_ashrrev_i32_e32 v1, 31, v0
	v_add_u32_e32 v3, v8, v3
	v_lshrrev_b32_e32 v1, 26, v1
	v_ashrrev_i32_e32 v13, 6, v3
	v_add_u32_e32 v1, v0, v1
	v_lshlrev_b32_e32 v3, 3, v13
	v_ashrrev_i32_e32 v12, 6, v1
	v_and_b32_e32 v3, -16, v3
	v_add_u32_e32 v3, v12, v3
	v_and_b32_e32 v4, 3, v12
	v_lshrrev_b32_e32 v5, 2, v3
	v_lshlrev_b32_e32 v6, 1, v3
	v_and_b32_e32 v1, 0xc0, v1
	v_and_or_b32 v4, v3, s2, v4
	v_and_b32_e32 v5, 4, v5
	v_and_b32_e32 v6, 24, v6
	v_sub_u32_e32 v0, v0, v1
	s_sub_i32 s4, 36, s6
	v_or3_b32 v4, v4, v5, v6
	v_lshlrev_b32_e32 v5, 5, v13
	v_ashrrev_i16_sdwa v0, v2, sext(v0) dst_sel:DWORD dst_unused:UNUSED_PAD src0_sel:DWORD src1_sel:BYTE_0
	s_min_u32 s7, s4, 8
	v_and_b32_e32 v5, 32, v5
	v_bfe_i32 v14, v0, 0, 16
	v_add_lshl_u32 v0, v5, v14, 1
	s_sext_i32_i16 s2, s1
	v_cvt_f32_ubyte0_e32 v2, s7
	v_lshl_add_u32 v132, v4, 12, v0
	v_cvt_f32_i32_e32 v1, s2
	v_rcp_iflag_f32_e32 v4, v2
	v_lshl_add_u32 v134, v3, 12, v0
	s_ashr_i32 s2, s2, 30
	s_or_b32 s2, s2, 1
	v_mul_f32_e32 v0, v1, v4
	v_trunc_f32_e32 v0, v0
	v_fma_f32 v1, -v0, v2, v1
	v_cvt_i32_f32_e32 v0, v0
	v_cmp_ge_f32_e64 s[4:5], |v1|, v2
	s_and_b64 s[4:5], s[4:5], exec
	s_cselect_b32 s2, s2, 0
	v_readfirstlane_b32 s4, v0
	s_add_i32 s2, s4, s2
	s_mul_i32 s4, s2, s7
	s_sub_i32 s1, s1, s4
	s_sext_i32_i16 s1, s1
	s_add_i32 s20, s6, s1
	s_ashr_i32 s21, s20, 31
	s_bfe_i64 s[6:7], s[2:3], 0x100000
	s_lshl_b64 s[4:5], s[20:21], 20
	s_lshl_b64 s[6:7], s[6:7], 20
	s_add_u32 s24, s29, s6
	s_addc_u32 s25, s30, s7
	s_add_i32 s21, s31, 0
	s_add_i32 m0, s21, 0x10000
	v_readlane_b32 s6, v247, 9
	s_lshl_b32 s98, s3, 17
	v_add_u32_e32 v132, s98, v132
	s_add_i32 s98, s98, 0x40000
	v_add_u32_e32 v128, s98, v128
	global_load_lds_dwordx4 v132, s[24:25]
	s_add_i32 m0, s21, 0x12000
	v_readlane_b32 s7, v247, 10
	s_add_u32 s22, s6, s4
	global_load_lds_dwordx4 v128, s[24:25]
	s_addc_u32 s23, s7, s5
	s_mov_b32 m0, s21
	s_add_i32 s35, s21, 0x2000
	global_load_lds_dwordx4 v134, s[22:23]
	s_mov_b32 m0, s35
	s_add_u32 s4, s24, 0x20000
	global_load_lds_dwordx4 v130, s[22:23]
	s_addc_u32 s5, s25, 0
	s_add_i32 m0, s21, 0x14000
	v_mov_b32_e32 v133, 0
	global_load_lds_dwordx4 v132, s[4:5]
	s_add_i32 m0, s21, 0x16000
	v_mov_b32_e32 v129, v133
	global_load_lds_dwordx4 v128, s[4:5]
	s_add_u32 s4, s22, 0x80000
	s_addc_u32 s5, s23, 0
	s_add_i32 s36, s21, 0x4000
	s_mov_b32 m0, s36
	s_add_i32 s37, s21, 0x6000
	global_load_lds_dwordx4 v134, s[4:5]
	s_mov_b32 m0, s37
	v_mov_b32_e32 v135, v133
	global_load_lds_dwordx4 v130, s[4:5]
	v_mov_b32_e32 v131, v133
	s_mov_b32 s38, 0
	v_lshl_add_u64 v[6:7], s[24:25], 0, v[132:133]
	v_lshl_add_u64 v[4:5], s[24:25], 0, v[128:129]
	v_lshl_add_u64 v[2:3], s[22:23], 0, v[134:135]
	s_cmp_lg_u32 s3, 1
	v_lshl_add_u64 v[0:1], s[22:23], 0, v[130:131]
	s_cbranch_scc1 .LBB0_1560
	s_barrier
.LBB0_1560:
	s_lshl_b32 s0, s0, 5
	s_and_b32 s7, s0, 0x60
	s_mov_b64 s[0:1], 0x80
	s_add_i32 m0, s21, 0x18000
	v_lshl_add_u64 v[6:7], v[6:7], 0, s[0:1]
	s_lshl_b32 s6, s3, 13
	s_lshl_b32 s8, s7, 7
	s_waitcnt vmcnt(4)
	s_barrier
	global_load_lds_dwordx4 v[6:7], off
	v_lshl_add_u64 v[4:5], v[4:5], 0, s[0:1]
	s_add_i32 m0, s21, 0x1a000
	s_add_i32 s39, s21, 0x8000
	s_add_i32 s40, s21, 0xa000
	global_load_lds_dwordx4 v[4:5], off
	v_lshl_add_u64 v[2:3], v[2:3], 0, s[0:1]
	s_mov_b32 m0, s39
	s_add_u32 s4, s24, 0x20080
	global_load_lds_dwordx4 v[2:3], off
	v_lshl_add_u64 v[0:1], v[0:1], 0, s[0:1]
	s_mov_b32 m0, s40
	s_addc_u32 s5, s25, 0
	global_load_lds_dwordx4 v[0:1], off
	s_add_i32 m0, s21, 0x1c000
	v_lshl_add_u64 v[0:1], s[4:5], 0, v[132:133]
	global_load_lds_dwordx4 v[0:1], off
	v_lshl_add_u64 v[0:1], s[4:5], 0, v[128:129]
	s_add_i32 m0, s21, 0x1e000
	s_add_i32 s41, 0, 0x10000
	global_load_lds_dwordx4 v[0:1], off
	v_lshrrev_b32_e32 v1, 1, v8
	v_and_b32_e32 v1, 24, v1
	v_and_b32_e32 v0, 15, v8
	v_lshlrev_b32_e32 v2, 1, v1
	v_lshl_or_b32 v146, s3, 6, v0
	v_lshl_or_b32 v0, v0, 6, v2
	v_lshlrev_b32_e32 v2, 2, v8
	v_and_b32_e32 v2, 32, v2
	v_bitop3_b32 v3, v0, s6, v2 bitop3:0xde
	v_bitop3_b32 v147, v0, s8, v2 bitop3:0xde
	v_lshlrev_b32_e32 v0, 15, v13
	v_and_b32_e32 v0, 0xffff0000, v0
	v_or_b32_e32 v148, s7, v1
	v_lshl_add_u32 v0, v12, 12, v0
	v_and_b32_e32 v1, 1, v13
	v_lshl_or_b32 v0, v1, 6, v0
	v_lshl_add_u32 v136, v14, 1, v0
	v_lshlrev_b32_e32 v0, 15, v9
	v_and_b32_e32 v0, 0xffff0000, v0
	s_waitcnt vmcnt(6)
	v_lshl_add_u32 v0, v10, 12, v0
	v_and_b32_e32 v1, 1, v9
	v_lshl_or_b32 v0, v1, 6, v0
	s_add_i32 s42, 0, 0x14000
	s_sext_i32_i16 s47, s2
	v_mov_b32_e32 v137, v133
	v_lshl_add_u32 v138, v11, 1, v0
	v_mov_b32_e32 v139, v133
	v_mov_b64_e32 v[140:141], 0x480
	v_mov_b64_e32 v[142:143], 0x47f
	v_add_u32_e32 v149, s41, v147
	v_add_u32_e32 v150, 0, v3
	v_add_u32_e32 v151, s42, v147
	s_mov_b64 s[4:5], 0x200000
	s_mov_b32 s43, 0x200000
	s_mov_b64 s[6:7], 0x240000
	s_mov_b32 s44, 0x240000
	s_mov_b64 s[8:9], 0x280000
	s_mov_b32 s45, 0x280000
	s_mov_b64 s[10:11], 0x2c0000
	s_mov_b32 s46, 0x2c0000
	s_barrier

.LBB0_1564:
	ds_read_b128 v[152:155], v149
	ds_read_b128 v[156:159], v149 offset:1024
	ds_read_b128 v[160:163], v149 offset:2048
	ds_read_b128 v[164:167], v149 offset:3072
	s_add_u32 s24, s22, 0xfff80080
	s_addc_u32 s25, s23, -1
	s_cmp_eq_u32 s52, 28
	s_cselect_b32 s27, s15, s25
	s_cselect_b32 s26, s48, s24
	s_cselect_b32 s25, s13, s51
	s_cselect_b32 s24, s49, s50
	v_lshl_add_u64 v[144:145], s[22:23], 0, v[136:137]
	s_add_i32 m0, s21, 0xc000
	ds_read_b128 v[168:171], v150
	ds_read_b128 v[172:175], v150 offset:1024
	ds_read_b128 v[176:179], v150 offset:2048
	ds_read_b128 v[180:183], v150 offset:3072
	ds_read_b128 v[184:187], v150 offset:4096
	ds_read_b128 v[188:191], v150 offset:5120
	ds_read_b128 v[192:195], v150 offset:6144
	ds_read_b128 v[196:199], v150 offset:7168
	global_load_lds_dwordx4 v[144:145], off
	v_lshl_add_u64 v[144:145], s[22:23], 0, v[138:139]
	s_add_i32 m0, s21, 0xe000
	s_nop 0
	global_load_lds_dwordx4 v[144:145], off
	s_waitcnt lgkmcnt(8)
	s_barrier
	s_waitcnt lgkmcnt(0)
	s_setprio 1
	s_waitcnt lgkmcnt(0)
	v_mfma_f32_16x16x32_bf16 v[124:127], v[152:155], v[168:171], v[124:127]
	v_mfma_f32_16x16x32_bf16 v[120:123], v[160:163], v[168:171], v[120:123]
	v_mfma_f32_16x16x32_bf16 v[108:111], v[152:155], v[176:179], v[108:111]
	v_mfma_f32_16x16x32_bf16 v[104:107], v[160:163], v[176:179], v[104:107]
	v_mfma_f32_16x16x32_bf16 v[92:95], v[152:155], v[184:187], v[92:95]
	v_mfma_f32_16x16x32_bf16 v[88:91], v[160:163], v[184:187], v[88:91]
	v_mfma_f32_16x16x32_bf16 v[76:79], v[152:155], v[192:195], v[76:79]
	v_mfma_f32_16x16x32_bf16 v[72:75], v[160:163], v[192:195], v[72:75]
	v_mfma_f32_16x16x32_bf16 v[124:127], v[156:159], v[172:175], v[124:127]
	v_mfma_f32_16x16x32_bf16 v[120:123], v[164:167], v[172:175], v[120:123]
	v_mfma_f32_16x16x32_bf16 v[108:111], v[156:159], v[180:183], v[108:111]
	v_mfma_f32_16x16x32_bf16 v[104:107], v[164:167], v[180:183], v[104:107]
	v_mfma_f32_16x16x32_bf16 v[92:95], v[156:159], v[188:191], v[92:95]
	v_mfma_f32_16x16x32_bf16 v[88:91], v[164:167], v[188:191], v[88:91]
	v_mfma_f32_16x16x32_bf16 v[76:79], v[156:159], v[196:199], v[76:79]
	v_mfma_f32_16x16x32_bf16 v[72:75], v[164:167], v[196:199], v[72:75]
	s_setprio 0
	s_barrier
	s_add_i32 s53, s41, s31
	v_lshl_add_u64 v[144:145], s[24:25], 0, v[132:133]
	s_mov_b32 m0, s53
	ds_read_b128 v[204:207], v151
	ds_read_b128 v[208:211], v151 offset:1024
	ds_read_b128 v[212:215], v151 offset:2048
	ds_read_b128 v[216:219], v151 offset:3072
	global_load_lds_dwordx4 v[144:145], off
	v_lshl_add_u64 v[200:201], s[24:25], 0, v[128:129]
	s_add_i32 m0, s53, 0x2000
	s_nop 0
	global_load_lds_dwordx4 v[200:201], off
	s_barrier
	s_waitcnt lgkmcnt(0)
	s_setprio 1
	s_waitcnt lgkmcnt(0)
	v_mfma_f32_16x16x32_bf16 v[116:119], v[204:207], v[168:171], v[116:119]
	v_mfma_f32_16x16x32_bf16 v[112:115], v[212:215], v[168:171], v[112:115]
	v_mfma_f32_16x16x32_bf16 v[100:103], v[204:207], v[176:179], v[100:103]
	v_mfma_f32_16x16x32_bf16 v[96:99], v[212:215], v[176:179], v[96:99]
	v_mfma_f32_16x16x32_bf16 v[84:87], v[204:207], v[184:187], v[84:87]
	v_mfma_f32_16x16x32_bf16 v[80:83], v[212:215], v[184:187], v[80:83]
	v_mfma_f32_16x16x32_bf16 v[68:71], v[204:207], v[192:195], v[68:71]
	v_mfma_f32_16x16x32_bf16 v[64:67], v[212:215], v[192:195], v[64:67]
	v_mfma_f32_16x16x32_bf16 v[116:119], v[208:211], v[172:175], v[116:119]
	v_mfma_f32_16x16x32_bf16 v[112:115], v[216:219], v[172:175], v[112:115]
	v_mfma_f32_16x16x32_bf16 v[100:103], v[208:211], v[180:183], v[100:103]
	v_mfma_f32_16x16x32_bf16 v[96:99], v[216:219], v[180:183], v[96:99]
	v_mfma_f32_16x16x32_bf16 v[84:87], v[208:211], v[188:191], v[84:87]
	v_mfma_f32_16x16x32_bf16 v[80:83], v[216:219], v[188:191], v[80:83]
	v_mfma_f32_16x16x32_bf16 v[68:71], v[208:211], v[196:199], v[68:71]
	v_mfma_f32_16x16x32_bf16 v[64:67], v[216:219], v[196:199], v[64:67]
	s_setprio 0
	s_mov_b32 m0, s21
	v_lshl_add_u64 v[220:221], s[26:27], 0, v[134:135]
	s_barrier
	ds_read_b128 v[168:171], v150 offset:16384
	ds_read_b128 v[172:175], v150 offset:17408
	ds_read_b128 v[176:179], v150 offset:18432
	ds_read_b128 v[180:183], v150 offset:19456
	ds_read_b128 v[184:187], v150 offset:20480
	ds_read_b128 v[188:191], v150 offset:21504
	ds_read_b128 v[192:195], v150 offset:22528
	ds_read_b128 v[196:199], v150 offset:23552
	global_load_lds_dwordx4 v[220:221], off
	v_lshl_add_u64 v[222:223], s[26:27], 0, v[130:131]
	s_mov_b32 m0, s35
	s_nop 0
	global_load_lds_dwordx4 v[222:223], off
	s_barrier
	s_waitcnt lgkmcnt(0)
	s_setprio 1
	s_waitcnt lgkmcnt(0)
	v_mfma_f32_16x16x32_bf16 v[60:63], v[152:155], v[168:171], v[60:63]
	v_mfma_f32_16x16x32_bf16 v[56:59], v[160:163], v[168:171], v[56:59]
	v_mfma_f32_16x16x32_bf16 v[44:47], v[152:155], v[176:179], v[44:47]
	v_mfma_f32_16x16x32_bf16 v[40:43], v[160:163], v[176:179], v[40:43]
	v_mfma_f32_16x16x32_bf16 v[28:31], v[152:155], v[184:187], v[28:31]
	v_mfma_f32_16x16x32_bf16 v[24:27], v[160:163], v[184:187], v[24:27]
	v_mfma_f32_16x16x32_bf16 v[12:15], v[152:155], v[192:195], v[12:15]
	v_mfma_f32_16x16x32_bf16 v[8:11], v[160:163], v[192:195], v[8:11]
	v_mfma_f32_16x16x32_bf16 v[60:63], v[156:159], v[172:175], v[60:63]
	v_mfma_f32_16x16x32_bf16 v[56:59], v[164:167], v[172:175], v[56:59]
	v_mfma_f32_16x16x32_bf16 v[44:47], v[156:159], v[180:183], v[44:47]
	v_mfma_f32_16x16x32_bf16 v[40:43], v[164:167], v[180:183], v[40:43]
	v_mfma_f32_16x16x32_bf16 v[28:31], v[156:159], v[188:191], v[28:31]
	v_mfma_f32_16x16x32_bf16 v[24:27], v[164:167], v[188:191], v[24:27]
	v_mfma_f32_16x16x32_bf16 v[12:15], v[156:159], v[196:199], v[12:15]
	v_mfma_f32_16x16x32_bf16 v[8:11], v[164:167], v[196:199], v[8:11]
	s_setprio 0
	s_barrier
	s_add_u32 s54, s24, 0x20000
	s_addc_u32 s55, s25, 0
	s_add_i32 s53, s42, s31
	v_lshl_add_u64 v[152:153], s[54:55], 0, v[132:133]
	s_mov_b32 m0, s53
	s_nop 0
	global_load_lds_dwordx4 v[152:153], off
	v_lshl_add_u64 v[152:153], s[54:55], 0, v[128:129]
	s_add_i32 m0, s53, 0x2000
	s_nop 0
	global_load_lds_dwordx4 v[152:153], off
	s_waitcnt vmcnt(6)
	s_barrier
	s_setprio 1
	v_mfma_f32_16x16x32_bf16 v[52:55], v[204:207], v[168:171], v[52:55]
	v_mfma_f32_16x16x32_bf16 v[48:51], v[212:215], v[168:171], v[48:51]
	v_mfma_f32_16x16x32_bf16 v[36:39], v[204:207], v[176:179], v[36:39]
	v_mfma_f32_16x16x32_bf16 v[32:35], v[212:215], v[176:179], v[32:35]
	v_mfma_f32_16x16x32_bf16 v[20:23], v[204:207], v[184:187], v[20:23]
	v_mfma_f32_16x16x32_bf16 v[16:19], v[212:215], v[184:187], v[16:19]
	v_mfma_f32_16x16x32_bf16 v[4:7], v[204:207], v[192:195], v[4:7]
	v_mfma_f32_16x16x32_bf16 v[0:3], v[212:215], v[192:195], v[0:3]
	v_mfma_f32_16x16x32_bf16 v[52:55], v[208:211], v[172:175], v[52:55]
	v_mfma_f32_16x16x32_bf16 v[48:51], v[216:219], v[172:175], v[48:51]
	v_mfma_f32_16x16x32_bf16 v[36:39], v[208:211], v[180:183], v[36:39]
	v_mfma_f32_16x16x32_bf16 v[32:35], v[216:219], v[180:183], v[32:35]
	v_mfma_f32_16x16x32_bf16 v[20:23], v[208:211], v[188:191], v[20:23]
	v_mfma_f32_16x16x32_bf16 v[16:19], v[216:219], v[188:191], v[16:19]
	v_mfma_f32_16x16x32_bf16 v[4:7], v[208:211], v[196:199], v[4:7]
	v_mfma_f32_16x16x32_bf16 v[0:3], v[216:219], v[196:199], v[0:3]
	s_setprio 0
	s_add_i32 s53, 0, 0x18000
	v_add_u32_e32 v164, s53, v147
	s_barrier
	ds_read_b128 v[152:155], v164
	ds_read_b128 v[156:159], v164 offset:1024
	ds_read_b128 v[160:163], v164 offset:2048
	ds_read_b128 v[164:167], v164 offset:3072
	s_add_u32 s26, s26, 0x80000
	s_addc_u32 s27, s27, 0
	s_mov_b32 m0, s36
	v_lshl_add_u64 v[204:205], s[26:27], 0, v[134:135]
	ds_read_b128 v[168:171], v150 offset:32768
	ds_read_b128 v[172:175], v150 offset:33792
	ds_read_b128 v[176:179], v150 offset:34816
	ds_read_b128 v[180:183], v150 offset:35840
	ds_read_b128 v[184:187], v150 offset:36864
	ds_read_b128 v[188:191], v150 offset:37888
	ds_read_b128 v[192:195], v150 offset:38912
	ds_read_b128 v[196:199], v150 offset:39936
	global_load_lds_dwordx4 v[204:205], off
	v_lshl_add_u64 v[204:205], s[26:27], 0, v[130:131]
	s_mov_b32 m0, s37
	s_nop 0
	global_load_lds_dwordx4 v[204:205], off
	s_waitcnt lgkmcnt(8)
	s_barrier
	s_waitcnt lgkmcnt(0)
	s_setprio 1
	s_waitcnt lgkmcnt(0)
	v_mfma_f32_16x16x32_bf16 v[124:127], v[152:155], v[168:171], v[124:127]
	v_mfma_f32_16x16x32_bf16 v[120:123], v[160:163], v[168:171], v[120:123]
	v_mfma_f32_16x16x32_bf16 v[108:111], v[152:155], v[176:179], v[108:111]
	v_mfma_f32_16x16x32_bf16 v[104:107], v[160:163], v[176:179], v[104:107]
	v_mfma_f32_16x16x32_bf16 v[92:95], v[152:155], v[184:187], v[92:95]
	v_mfma_f32_16x16x32_bf16 v[88:91], v[160:163], v[184:187], v[88:91]
	v_mfma_f32_16x16x32_bf16 v[76:79], v[152:155], v[192:195], v[76:79]
	v_mfma_f32_16x16x32_bf16 v[72:75], v[160:163], v[192:195], v[72:75]
	v_mfma_f32_16x16x32_bf16 v[124:127], v[156:159], v[172:175], v[124:127]
	v_mfma_f32_16x16x32_bf16 v[120:123], v[164:167], v[172:175], v[120:123]
	v_mfma_f32_16x16x32_bf16 v[108:111], v[156:159], v[180:183], v[108:111]
	v_mfma_f32_16x16x32_bf16 v[104:107], v[164:167], v[180:183], v[104:107]
	v_mfma_f32_16x16x32_bf16 v[92:95], v[156:159], v[188:191], v[92:95]
	v_mfma_f32_16x16x32_bf16 v[88:91], v[164:167], v[188:191], v[88:91]
	v_mfma_f32_16x16x32_bf16 v[76:79], v[156:159], v[196:199], v[76:79]
	v_mfma_f32_16x16x32_bf16 v[72:75], v[164:167], v[196:199], v[72:75]
	s_setprio 0
	s_barrier
	s_add_i32 s26, 0, 0x1c000
	s_add_i32 s27, s53, s31
	v_add_u32_e32 v216, s26, v147
	v_lshl_add_u64 v[144:145], v[144:145], 0, s[0:1]
	s_mov_b32 m0, s27
	ds_read_b128 v[204:207], v216
	ds_read_b128 v[208:211], v216 offset:1024
	ds_read_b128 v[212:215], v216 offset:2048
	ds_read_b128 v[216:219], v216 offset:3072
	global_load_lds_dwordx4 v[144:145], off
	v_lshl_add_u64 v[144:145], v[200:201], 0, s[0:1]
	s_add_i32 m0, s27, 0x2000
	s_nop 0
	global_load_lds_dwordx4 v[144:145], off
	s_barrier
	s_waitcnt lgkmcnt(0)
	s_setprio 1
	s_waitcnt lgkmcnt(0)
	v_mfma_f32_16x16x32_bf16 v[116:119], v[204:207], v[168:171], v[116:119]
	v_mfma_f32_16x16x32_bf16 v[112:115], v[212:215], v[168:171], v[112:115]
	v_mfma_f32_16x16x32_bf16 v[100:103], v[204:207], v[176:179], v[100:103]
	v_mfma_f32_16x16x32_bf16 v[96:99], v[212:215], v[176:179], v[96:99]
	v_mfma_f32_16x16x32_bf16 v[84:87], v[204:207], v[184:187], v[84:87]
	v_mfma_f32_16x16x32_bf16 v[80:83], v[212:215], v[184:187], v[80:83]
	v_mfma_f32_16x16x32_bf16 v[68:71], v[204:207], v[192:195], v[68:71]
	v_mfma_f32_16x16x32_bf16 v[64:67], v[212:215], v[192:195], v[64:67]
	v_mfma_f32_16x16x32_bf16 v[116:119], v[208:211], v[172:175], v[116:119]
	v_mfma_f32_16x16x32_bf16 v[112:115], v[216:219], v[172:175], v[112:115]
	v_mfma_f32_16x16x32_bf16 v[100:103], v[208:211], v[180:183], v[100:103]
	v_mfma_f32_16x16x32_bf16 v[96:99], v[216:219], v[180:183], v[96:99]
	v_mfma_f32_16x16x32_bf16 v[84:87], v[208:211], v[188:191], v[84:87]
	v_mfma_f32_16x16x32_bf16 v[80:83], v[216:219], v[188:191], v[80:83]
	v_mfma_f32_16x16x32_bf16 v[68:71], v[208:211], v[196:199], v[68:71]
	v_mfma_f32_16x16x32_bf16 v[64:67], v[216:219], v[196:199], v[64:67]
	s_setprio 0
	s_mov_b32 m0, s39
	v_lshl_add_u64 v[144:145], v[220:221], 0, s[0:1]
	s_barrier
	ds_read_b128 v[168:171], v150 offset:49152
	ds_read_b128 v[172:175], v150 offset:50176
	ds_read_b128 v[176:179], v150 offset:51200
	ds_read_b128 v[180:183], v150 offset:52224
	ds_read_b128 v[184:187], v150 offset:53248
	ds_read_b128 v[188:191], v150 offset:54272
	ds_read_b128 v[192:195], v150 offset:55296
	ds_read_b128 v[196:199], v150 offset:56320
	global_load_lds_dwordx4 v[144:145], off
	v_lshl_add_u64 v[144:145], v[222:223], 0, s[0:1]
	s_mov_b32 m0, s40
	s_nop 0
	global_load_lds_dwordx4 v[144:145], off
	s_barrier
	s_waitcnt lgkmcnt(0)
	s_setprio 1
	s_waitcnt lgkmcnt(0)
	v_mfma_f32_16x16x32_bf16 v[60:63], v[152:155], v[168:171], v[60:63]
	v_mfma_f32_16x16x32_bf16 v[56:59], v[160:163], v[168:171], v[56:59]
	v_mfma_f32_16x16x32_bf16 v[44:47], v[152:155], v[176:179], v[44:47]
	v_mfma_f32_16x16x32_bf16 v[40:43], v[160:163], v[176:179], v[40:43]
	v_mfma_f32_16x16x32_bf16 v[28:31], v[152:155], v[184:187], v[28:31]
	v_mfma_f32_16x16x32_bf16 v[24:27], v[160:163], v[184:187], v[24:27]
	v_mfma_f32_16x16x32_bf16 v[12:15], v[152:155], v[192:195], v[12:15]
	v_mfma_f32_16x16x32_bf16 v[8:11], v[160:163], v[192:195], v[8:11]
	v_mfma_f32_16x16x32_bf16 v[60:63], v[156:159], v[172:175], v[60:63]
	v_mfma_f32_16x16x32_bf16 v[56:59], v[164:167], v[172:175], v[56:59]
	v_mfma_f32_16x16x32_bf16 v[44:47], v[156:159], v[180:183], v[44:47]
	v_mfma_f32_16x16x32_bf16 v[40:43], v[164:167], v[180:183], v[40:43]
	v_mfma_f32_16x16x32_bf16 v[28:31], v[156:159], v[188:191], v[28:31]
	v_mfma_f32_16x16x32_bf16 v[24:27], v[164:167], v[188:191], v[24:27]
	v_mfma_f32_16x16x32_bf16 v[12:15], v[156:159], v[196:199], v[12:15]
	v_mfma_f32_16x16x32_bf16 v[8:11], v[164:167], v[196:199], v[8:11]
	s_setprio 0
	s_barrier
	s_add_u32 s24, s24, 0x20080
	s_addc_u32 s25, s25, 0
	s_add_i32 s26, s26, s31
	v_lshl_add_u64 v[144:145], s[24:25], 0, v[132:133]
	s_mov_b32 m0, s26
	s_nop 0
	global_load_lds_dwordx4 v[144:145], off
	v_lshl_add_u64 v[144:145], s[24:25], 0, v[128:129]
	s_add_i32 m0, s26, 0x2000
	s_nop 0
	global_load_lds_dwordx4 v[144:145], off
	s_waitcnt vmcnt(6)
	s_barrier
	s_setprio 1
	v_mfma_f32_16x16x32_bf16 v[52:55], v[204:207], v[168:171], v[52:55]
	v_mfma_f32_16x16x32_bf16 v[48:51], v[212:215], v[168:171], v[48:51]
	v_mfma_f32_16x16x32_bf16 v[36:39], v[204:207], v[176:179], v[36:39]
	v_mfma_f32_16x16x32_bf16 v[32:35], v[212:215], v[176:179], v[32:35]
	v_mfma_f32_16x16x32_bf16 v[20:23], v[204:207], v[184:187], v[20:23]
	v_mfma_f32_16x16x32_bf16 v[16:19], v[212:215], v[184:187], v[16:19]
	v_mfma_f32_16x16x32_bf16 v[4:7], v[204:207], v[192:195], v[4:7]
	v_mfma_f32_16x16x32_bf16 v[0:3], v[212:215], v[192:195], v[0:3]
	v_mfma_f32_16x16x32_bf16 v[52:55], v[208:211], v[172:175], v[52:55]
	v_mfma_f32_16x16x32_bf16 v[48:51], v[216:219], v[172:175], v[48:51]
	v_mfma_f32_16x16x32_bf16 v[36:39], v[208:211], v[180:183], v[36:39]
	v_mfma_f32_16x16x32_bf16 v[32:35], v[216:219], v[180:183], v[32:35]
	v_mfma_f32_16x16x32_bf16 v[20:23], v[208:211], v[188:191], v[20:23]
	v_mfma_f32_16x16x32_bf16 v[16:19], v[216:219], v[188:191], v[16:19]
	v_mfma_f32_16x16x32_bf16 v[4:7], v[208:211], v[196:199], v[4:7]
	v_mfma_f32_16x16x32_bf16 v[0:3], v[216:219], v[196:199], v[0:3]
	s_setprio 0
	s_add_i32 s52, s52, 2
	s_add_u32 s22, s22, 0x100
	s_addc_u32 s23, s23, 0
	s_add_u32 s50, s50, 0x100
	s_addc_u32 s51, s51, 0
	s_cmp_gt_u32 s52, 29
	s_barrier
	s_cbranch_scc0 .LBB0_1564
	v_readlane_b32 s100, v248, 63
	v_readlane_b32 s101, v247, 0
	v_and_b32_e32 v224, 15, v202
	v_bfe_u32 v225, v202, 4, 2
	v_bfe_u32 v226, v202, 6, 2
	v_lshrrev_b32_e32 v227, 8, v202
	v_and_b32_e32 v240, 7, v224
	v_lshl_add_u32 v240, v227, 6, v240
	v_lshl_add_u32 v240, s20, 8, v240
	v_lshlrev_b32_e32 v240, 14, v240
	v_lshrrev_b32_e32 v241, 3, v224
	v_lshlrev_b32_e32 v241, 6, v241
	v_lshl_add_u32 v241, v226, 7, v241
	v_lshl_add_u32 v241, v225, 4, v241
	v_add_u32_e32 v240, v240, v241
	s_lshl_b32 s98, s47, 9
	v_add_u32_e32 v240, s98, v240
	v_max_f32_e32 v124, 0, v124
	v_max_f32_e32 v125, 0, v125
	v_max_f32_e32 v126, 0, v126
	v_max_f32_e32 v127, 0, v127
	v_max_f32_e32 v120, 0, v120
	v_max_f32_e32 v121, 0, v121
	v_max_f32_e32 v122, 0, v122
	v_max_f32_e32 v123, 0, v123
	v_pk_mul_f32 v[124:125], v[124:125], v[124:125]
	v_pk_mul_f32 v[126:127], v[126:127], v[126:127]
	v_pk_mul_f32 v[120:121], v[120:121], v[120:121]
	v_pk_mul_f32 v[122:123], v[122:123], v[122:123]
	v_cvt_pk_bf16_f32 v228, v124, v125
	v_cvt_pk_bf16_f32 v229, v126, v127
	v_cvt_pk_bf16_f32 v230, v120, v121
	v_cvt_pk_bf16_f32 v231, v122, v123
	v_max_f32_e32 v116, 0, v116
	v_max_f32_e32 v117, 0, v117
	v_max_f32_e32 v118, 0, v118
	v_max_f32_e32 v119, 0, v119
	v_max_f32_e32 v112, 0, v112
	v_max_f32_e32 v113, 0, v113
	v_max_f32_e32 v114, 0, v114
	v_max_f32_e32 v115, 0, v115
	v_pk_mul_f32 v[116:117], v[116:117], v[116:117]
	v_pk_mul_f32 v[118:119], v[118:119], v[118:119]
	v_pk_mul_f32 v[112:113], v[112:113], v[112:113]
	v_pk_mul_f32 v[114:115], v[114:115], v[114:115]
	v_cvt_pk_bf16_f32 v232, v116, v117
	v_cvt_pk_bf16_f32 v233, v118, v119
	v_cvt_pk_bf16_f32 v234, v112, v113
	v_cvt_pk_bf16_f32 v235, v114, v115
	v_mov_b32_e32 v236, v228
	v_mov_b32_e32 v237, v229
	v_mov_b32_e32 v238, v230
	v_mov_b32_e32 v239, v231
	v_mov_b32_dpp v228, v232 row_ror:8 row_mask:0xf bank_mask:0xc
	v_mov_b32_dpp v229, v233 row_ror:8 row_mask:0xf bank_mask:0xc
	v_mov_b32_dpp v230, v234 row_ror:8 row_mask:0xf bank_mask:0xc
	v_mov_b32_dpp v231, v235 row_ror:8 row_mask:0xf bank_mask:0xc
	v_mov_b32_dpp v232, v236 row_ror:8 row_mask:0xf bank_mask:0x3
	v_mov_b32_dpp v233, v237 row_ror:8 row_mask:0xf bank_mask:0x3
	v_mov_b32_dpp v234, v238 row_ror:8 row_mask:0xf bank_mask:0x3
	v_mov_b32_dpp v235, v239 row_ror:8 row_mask:0xf bank_mask:0x3
	global_store_dwordx4 v240, v[228:231], s[100:101]
	s_add_u32 s100, s100, 0x20000
	s_addc_u32 s101, s101, 0
	global_store_dwordx4 v240, v[232:235], s[100:101]
	v_max_f32_e32 v108, 0, v108
	v_max_f32_e32 v109, 0, v109
	v_max_f32_e32 v110, 0, v110
	v_max_f32_e32 v111, 0, v111
	v_max_f32_e32 v104, 0, v104
	v_max_f32_e32 v105, 0, v105
	v_max_f32_e32 v106, 0, v106
	v_max_f32_e32 v107, 0, v107
	v_pk_mul_f32 v[108:109], v[108:109], v[108:109]
	v_pk_mul_f32 v[110:111], v[110:111], v[110:111]
	v_pk_mul_f32 v[104:105], v[104:105], v[104:105]
	v_pk_mul_f32 v[106:107], v[106:107], v[106:107]
	v_cvt_pk_bf16_f32 v228, v108, v109
	v_cvt_pk_bf16_f32 v229, v110, v111
	v_cvt_pk_bf16_f32 v230, v104, v105
	v_cvt_pk_bf16_f32 v231, v106, v107
	v_max_f32_e32 v100, 0, v100
	v_max_f32_e32 v101, 0, v101
	v_max_f32_e32 v102, 0, v102
	v_max_f32_e32 v103, 0, v103
	v_max_f32_e32 v96, 0, v96
	v_max_f32_e32 v97, 0, v97
	v_max_f32_e32 v98, 0, v98
	v_max_f32_e32 v99, 0, v99
	v_pk_mul_f32 v[100:101], v[100:101], v[100:101]
	v_pk_mul_f32 v[102:103], v[102:103], v[102:103]
	v_pk_mul_f32 v[96:97], v[96:97], v[96:97]
	v_pk_mul_f32 v[98:99], v[98:99], v[98:99]
	v_cvt_pk_bf16_f32 v232, v100, v101
	v_cvt_pk_bf16_f32 v233, v102, v103
	v_cvt_pk_bf16_f32 v234, v96, v97
	v_cvt_pk_bf16_f32 v235, v98, v99
	v_mov_b32_e32 v236, v228
	v_mov_b32_e32 v237, v229
	v_mov_b32_e32 v238, v230
	v_mov_b32_e32 v239, v231
	v_mov_b32_dpp v228, v232 row_ror:8 row_mask:0xf bank_mask:0xc
	v_mov_b32_dpp v229, v233 row_ror:8 row_mask:0xf bank_mask:0xc
	v_mov_b32_dpp v230, v234 row_ror:8 row_mask:0xf bank_mask:0xc
	v_mov_b32_dpp v231, v235 row_ror:8 row_mask:0xf bank_mask:0xc
	v_mov_b32_dpp v232, v236 row_ror:8 row_mask:0xf bank_mask:0x3
	v_mov_b32_dpp v233, v237 row_ror:8 row_mask:0xf bank_mask:0x3
	v_mov_b32_dpp v234, v238 row_ror:8 row_mask:0xf bank_mask:0x3
	v_mov_b32_dpp v235, v239 row_ror:8 row_mask:0xf bank_mask:0x3
	s_add_u32 s100, s100, 0x20000
	s_addc_u32 s101, s101, 0
	global_store_dwordx4 v240, v[228:231], s[100:101]
	s_add_u32 s100, s100, 0x20000
	s_addc_u32 s101, s101, 0
	global_store_dwordx4 v240, v[232:235], s[100:101]
	v_max_f32_e32 v92, 0, v92
	v_max_f32_e32 v93, 0, v93
	v_max_f32_e32 v94, 0, v94
	v_max_f32_e32 v95, 0, v95
	v_max_f32_e32 v88, 0, v88
	v_max_f32_e32 v89, 0, v89
	v_max_f32_e32 v90, 0, v90
	v_max_f32_e32 v91, 0, v91
	v_pk_mul_f32 v[92:93], v[92:93], v[92:93]
	v_pk_mul_f32 v[94:95], v[94:95], v[94:95]
	v_pk_mul_f32 v[88:89], v[88:89], v[88:89]
	v_pk_mul_f32 v[90:91], v[90:91], v[90:91]
	v_cvt_pk_bf16_f32 v228, v92, v93
	v_cvt_pk_bf16_f32 v229, v94, v95
	v_cvt_pk_bf16_f32 v230, v88, v89
	v_cvt_pk_bf16_f32 v231, v90, v91
	v_max_f32_e32 v84, 0, v84
	v_max_f32_e32 v85, 0, v85
	v_max_f32_e32 v86, 0, v86
	v_max_f32_e32 v87, 0, v87
	v_max_f32_e32 v80, 0, v80
	v_max_f32_e32 v81, 0, v81
	v_max_f32_e32 v82, 0, v82
	v_max_f32_e32 v83, 0, v83
	v_pk_mul_f32 v[84:85], v[84:85], v[84:85]
	v_pk_mul_f32 v[86:87], v[86:87], v[86:87]
	v_pk_mul_f32 v[80:81], v[80:81], v[80:81]
	v_pk_mul_f32 v[82:83], v[82:83], v[82:83]
	v_cvt_pk_bf16_f32 v232, v84, v85
	v_cvt_pk_bf16_f32 v233, v86, v87
	v_cvt_pk_bf16_f32 v234, v80, v81
	v_cvt_pk_bf16_f32 v235, v82, v83
	v_mov_b32_e32 v236, v228
	v_mov_b32_e32 v237, v229
	v_mov_b32_e32 v238, v230
	v_mov_b32_e32 v239, v231
	v_mov_b32_dpp v228, v232 row_ror:8 row_mask:0xf bank_mask:0xc
	v_mov_b32_dpp v229, v233 row_ror:8 row_mask:0xf bank_mask:0xc
	v_mov_b32_dpp v230, v234 row_ror:8 row_mask:0xf bank_mask:0xc
	v_mov_b32_dpp v231, v235 row_ror:8 row_mask:0xf bank_mask:0xc
	v_mov_b32_dpp v232, v236 row_ror:8 row_mask:0xf bank_mask:0x3
	v_mov_b32_dpp v233, v237 row_ror:8 row_mask:0xf bank_mask:0x3
	v_mov_b32_dpp v234, v238 row_ror:8 row_mask:0xf bank_mask:0x3
	v_mov_b32_dpp v235, v239 row_ror:8 row_mask:0xf bank_mask:0x3
	s_add_u32 s100, s100, 0x20000
	s_addc_u32 s101, s101, 0
	global_store_dwordx4 v240, v[228:231], s[100:101]
	s_add_u32 s100, s100, 0x20000
	s_addc_u32 s101, s101, 0
	global_store_dwordx4 v240, v[232:235], s[100:101]
	v_max_f32_e32 v76, 0, v76
	v_max_f32_e32 v77, 0, v77
	v_max_f32_e32 v78, 0, v78
	v_max_f32_e32 v79, 0, v79
	v_max_f32_e32 v72, 0, v72
	v_max_f32_e32 v73, 0, v73
	v_max_f32_e32 v74, 0, v74
	v_max_f32_e32 v75, 0, v75
	v_pk_mul_f32 v[76:77], v[76:77], v[76:77]
	v_pk_mul_f32 v[78:79], v[78:79], v[78:79]
	v_pk_mul_f32 v[72:73], v[72:73], v[72:73]
	v_pk_mul_f32 v[74:75], v[74:75], v[74:75]
	v_cvt_pk_bf16_f32 v228, v76, v77
	v_cvt_pk_bf16_f32 v229, v78, v79
	v_cvt_pk_bf16_f32 v230, v72, v73
	v_cvt_pk_bf16_f32 v231, v74, v75
	v_max_f32_e32 v68, 0, v68
	v_max_f32_e32 v69, 0, v69
	v_max_f32_e32 v70, 0, v70
	v_max_f32_e32 v71, 0, v71
	v_max_f32_e32 v64, 0, v64
	v_max_f32_e32 v65, 0, v65
	v_max_f32_e32 v66, 0, v66
	v_max_f32_e32 v67, 0, v67
	v_pk_mul_f32 v[68:69], v[68:69], v[68:69]
	v_pk_mul_f32 v[70:71], v[70:71], v[70:71]
	v_pk_mul_f32 v[64:65], v[64:65], v[64:65]
	v_pk_mul_f32 v[66:67], v[66:67], v[66:67]
	v_cvt_pk_bf16_f32 v232, v68, v69
	v_cvt_pk_bf16_f32 v233, v70, v71
	v_cvt_pk_bf16_f32 v234, v64, v65
	v_cvt_pk_bf16_f32 v235, v66, v67
	v_mov_b32_e32 v236, v228
	v_mov_b32_e32 v237, v229
	v_mov_b32_e32 v238, v230
	v_mov_b32_e32 v239, v231
	v_mov_b32_dpp v228, v232 row_ror:8 row_mask:0xf bank_mask:0xc
	v_mov_b32_dpp v229, v233 row_ror:8 row_mask:0xf bank_mask:0xc
	v_mov_b32_dpp v230, v234 row_ror:8 row_mask:0xf bank_mask:0xc
	v_mov_b32_dpp v231, v235 row_ror:8 row_mask:0xf bank_mask:0xc
	v_mov_b32_dpp v232, v236 row_ror:8 row_mask:0xf bank_mask:0x3
	v_mov_b32_dpp v233, v237 row_ror:8 row_mask:0xf bank_mask:0x3
	v_mov_b32_dpp v234, v238 row_ror:8 row_mask:0xf bank_mask:0x3
	v_mov_b32_dpp v235, v239 row_ror:8 row_mask:0xf bank_mask:0x3
	s_add_u32 s100, s100, 0x20000
	s_addc_u32 s101, s101, 0
	global_store_dwordx4 v240, v[228:231], s[100:101]
	s_add_u32 s100, s100, 0x20000
	s_addc_u32 s101, s101, 0
	global_store_dwordx4 v240, v[232:235], s[100:101]
	v_max_f32_e32 v60, 0, v60
	v_max_f32_e32 v61, 0, v61
	v_max_f32_e32 v62, 0, v62
	v_max_f32_e32 v63, 0, v63
	v_max_f32_e32 v56, 0, v56
	v_max_f32_e32 v57, 0, v57
	v_max_f32_e32 v58, 0, v58
	v_max_f32_e32 v59, 0, v59
	v_pk_mul_f32 v[60:61], v[60:61], v[60:61]
	v_pk_mul_f32 v[62:63], v[62:63], v[62:63]
	v_pk_mul_f32 v[56:57], v[56:57], v[56:57]
	v_pk_mul_f32 v[58:59], v[58:59], v[58:59]
	v_cvt_pk_bf16_f32 v228, v60, v61
	v_cvt_pk_bf16_f32 v229, v62, v63
	v_cvt_pk_bf16_f32 v230, v56, v57
	v_cvt_pk_bf16_f32 v231, v58, v59
	v_max_f32_e32 v52, 0, v52
	v_max_f32_e32 v53, 0, v53
	v_max_f32_e32 v54, 0, v54
	v_max_f32_e32 v55, 0, v55
	v_max_f32_e32 v48, 0, v48
	v_max_f32_e32 v49, 0, v49
	v_max_f32_e32 v50, 0, v50
	v_max_f32_e32 v51, 0, v51
	v_pk_mul_f32 v[52:53], v[52:53], v[52:53]
	v_pk_mul_f32 v[54:55], v[54:55], v[54:55]
	v_pk_mul_f32 v[48:49], v[48:49], v[48:49]
	v_pk_mul_f32 v[50:51], v[50:51], v[50:51]
	v_cvt_pk_bf16_f32 v232, v52, v53
	v_cvt_pk_bf16_f32 v233, v54, v55
	v_cvt_pk_bf16_f32 v234, v48, v49
	v_cvt_pk_bf16_f32 v235, v50, v51
	v_mov_b32_e32 v236, v228
	v_mov_b32_e32 v237, v229
	v_mov_b32_e32 v238, v230
	v_mov_b32_e32 v239, v231
	v_mov_b32_dpp v228, v232 row_ror:8 row_mask:0xf bank_mask:0xc
	v_mov_b32_dpp v229, v233 row_ror:8 row_mask:0xf bank_mask:0xc
	v_mov_b32_dpp v230, v234 row_ror:8 row_mask:0xf bank_mask:0xc
	v_mov_b32_dpp v231, v235 row_ror:8 row_mask:0xf bank_mask:0xc
	v_mov_b32_dpp v232, v236 row_ror:8 row_mask:0xf bank_mask:0x3
	v_mov_b32_dpp v233, v237 row_ror:8 row_mask:0xf bank_mask:0x3
	v_mov_b32_dpp v234, v238 row_ror:8 row_mask:0xf bank_mask:0x3
	v_mov_b32_dpp v235, v239 row_ror:8 row_mask:0xf bank_mask:0x3
	s_add_u32 s100, s100, 0x120000
	s_addc_u32 s101, s101, 0
	global_store_dwordx4 v240, v[228:231], s[100:101]
	s_add_u32 s100, s100, 0x20000
	s_addc_u32 s101, s101, 0
	global_store_dwordx4 v240, v[232:235], s[100:101]
	v_max_f32_e32 v44, 0, v44
	v_max_f32_e32 v45, 0, v45
	v_max_f32_e32 v46, 0, v46
	v_max_f32_e32 v47, 0, v47
	v_max_f32_e32 v40, 0, v40
	v_max_f32_e32 v41, 0, v41
	v_max_f32_e32 v42, 0, v42
	v_max_f32_e32 v43, 0, v43
	v_pk_mul_f32 v[44:45], v[44:45], v[44:45]
	v_pk_mul_f32 v[46:47], v[46:47], v[46:47]
	v_pk_mul_f32 v[40:41], v[40:41], v[40:41]
	v_pk_mul_f32 v[42:43], v[42:43], v[42:43]
	v_cvt_pk_bf16_f32 v228, v44, v45
	v_cvt_pk_bf16_f32 v229, v46, v47
	v_cvt_pk_bf16_f32 v230, v40, v41
	v_cvt_pk_bf16_f32 v231, v42, v43
	v_max_f32_e32 v36, 0, v36
	v_max_f32_e32 v37, 0, v37
	v_max_f32_e32 v38, 0, v38
	v_max_f32_e32 v39, 0, v39
	v_max_f32_e32 v32, 0, v32
	v_max_f32_e32 v33, 0, v33
	v_max_f32_e32 v34, 0, v34
	v_max_f32_e32 v35, 0, v35
	v_pk_mul_f32 v[36:37], v[36:37], v[36:37]
	v_pk_mul_f32 v[38:39], v[38:39], v[38:39]
	v_pk_mul_f32 v[32:33], v[32:33], v[32:33]
	v_pk_mul_f32 v[34:35], v[34:35], v[34:35]
	v_cvt_pk_bf16_f32 v232, v36, v37
	v_cvt_pk_bf16_f32 v233, v38, v39
	v_cvt_pk_bf16_f32 v234, v32, v33
	v_cvt_pk_bf16_f32 v235, v34, v35
	v_mov_b32_e32 v236, v228
	v_mov_b32_e32 v237, v229
	v_mov_b32_e32 v238, v230
	v_mov_b32_e32 v239, v231
	v_mov_b32_dpp v228, v232 row_ror:8 row_mask:0xf bank_mask:0xc
	v_mov_b32_dpp v229, v233 row_ror:8 row_mask:0xf bank_mask:0xc
	v_mov_b32_dpp v230, v234 row_ror:8 row_mask:0xf bank_mask:0xc
	v_mov_b32_dpp v231, v235 row_ror:8 row_mask:0xf bank_mask:0xc
	v_mov_b32_dpp v232, v236 row_ror:8 row_mask:0xf bank_mask:0x3
	v_mov_b32_dpp v233, v237 row_ror:8 row_mask:0xf bank_mask:0x3
	v_mov_b32_dpp v234, v238 row_ror:8 row_mask:0xf bank_mask:0x3
	v_mov_b32_dpp v235, v239 row_ror:8 row_mask:0xf bank_mask:0x3
	s_add_u32 s100, s100, 0x20000
	s_addc_u32 s101, s101, 0
	global_store_dwordx4 v240, v[228:231], s[100:101]
	s_add_u32 s100, s100, 0x20000
	s_addc_u32 s101, s101, 0
	global_store_dwordx4 v240, v[232:235], s[100:101]
	v_max_f32_e32 v28, 0, v28
	v_max_f32_e32 v29, 0, v29
	v_max_f32_e32 v30, 0, v30
	v_max_f32_e32 v31, 0, v31
	v_max_f32_e32 v24, 0, v24
	v_max_f32_e32 v25, 0, v25
	v_max_f32_e32 v26, 0, v26
	v_max_f32_e32 v27, 0, v27
	v_pk_mul_f32 v[28:29], v[28:29], v[28:29]
	v_pk_mul_f32 v[30:31], v[30:31], v[30:31]
	v_pk_mul_f32 v[24:25], v[24:25], v[24:25]
	v_pk_mul_f32 v[26:27], v[26:27], v[26:27]
	v_cvt_pk_bf16_f32 v228, v28, v29
	v_cvt_pk_bf16_f32 v229, v30, v31
	v_cvt_pk_bf16_f32 v230, v24, v25
	v_cvt_pk_bf16_f32 v231, v26, v27
	v_max_f32_e32 v20, 0, v20
	v_max_f32_e32 v21, 0, v21
	v_max_f32_e32 v22, 0, v22
	v_max_f32_e32 v23, 0, v23
	v_max_f32_e32 v16, 0, v16
	v_max_f32_e32 v17, 0, v17
	v_max_f32_e32 v18, 0, v18
	v_max_f32_e32 v19, 0, v19
	v_pk_mul_f32 v[20:21], v[20:21], v[20:21]
	v_pk_mul_f32 v[22:23], v[22:23], v[22:23]
	v_pk_mul_f32 v[16:17], v[16:17], v[16:17]
	v_pk_mul_f32 v[18:19], v[18:19], v[18:19]
	v_cvt_pk_bf16_f32 v232, v20, v21
	v_cvt_pk_bf16_f32 v233, v22, v23
	v_cvt_pk_bf16_f32 v234, v16, v17
	v_cvt_pk_bf16_f32 v235, v18, v19
	v_mov_b32_e32 v236, v228
	v_mov_b32_e32 v237, v229
	v_mov_b32_e32 v238, v230
	v_mov_b32_e32 v239, v231
	v_mov_b32_dpp v228, v232 row_ror:8 row_mask:0xf bank_mask:0xc
	v_mov_b32_dpp v229, v233 row_ror:8 row_mask:0xf bank_mask:0xc
	v_mov_b32_dpp v230, v234 row_ror:8 row_mask:0xf bank_mask:0xc
	v_mov_b32_dpp v231, v235 row_ror:8 row_mask:0xf bank_mask:0xc
	v_mov_b32_dpp v232, v236 row_ror:8 row_mask:0xf bank_mask:0x3
	v_mov_b32_dpp v233, v237 row_ror:8 row_mask:0xf bank_mask:0x3
	v_mov_b32_dpp v234, v238 row_ror:8 row_mask:0xf bank_mask:0x3
	v_mov_b32_dpp v235, v239 row_ror:8 row_mask:0xf bank_mask:0x3
	s_add_u32 s100, s100, 0x20000
	s_addc_u32 s101, s101, 0
	global_store_dwordx4 v240, v[228:231], s[100:101]
	s_add_u32 s100, s100, 0x20000
	s_addc_u32 s101, s101, 0
	global_store_dwordx4 v240, v[232:235], s[100:101]
	v_max_f32_e32 v12, 0, v12
	v_max_f32_e32 v13, 0, v13
	v_max_f32_e32 v14, 0, v14
	v_max_f32_e32 v15, 0, v15
	v_max_f32_e32 v8, 0, v8
	v_max_f32_e32 v9, 0, v9
	v_max_f32_e32 v10, 0, v10
	v_max_f32_e32 v11, 0, v11
	v_pk_mul_f32 v[12:13], v[12:13], v[12:13]
	v_pk_mul_f32 v[14:15], v[14:15], v[14:15]
	v_pk_mul_f32 v[8:9], v[8:9], v[8:9]
	v_pk_mul_f32 v[10:11], v[10:11], v[10:11]
	v_cvt_pk_bf16_f32 v228, v12, v13
	v_cvt_pk_bf16_f32 v229, v14, v15
	v_cvt_pk_bf16_f32 v230, v8, v9
	v_cvt_pk_bf16_f32 v231, v10, v11
	v_max_f32_e32 v4, 0, v4
	v_max_f32_e32 v5, 0, v5
	v_max_f32_e32 v6, 0, v6
	v_max_f32_e32 v7, 0, v7
	v_max_f32_e32 v0, 0, v0
	v_max_f32_e32 v1, 0, v1
	v_max_f32_e32 v2, 0, v2
	v_max_f32_e32 v3, 0, v3
	v_pk_mul_f32 v[4:5], v[4:5], v[4:5]
	v_pk_mul_f32 v[6:7], v[6:7], v[6:7]
	v_pk_mul_f32 v[0:1], v[0:1], v[0:1]
	v_pk_mul_f32 v[2:3], v[2:3], v[2:3]
	v_cvt_pk_bf16_f32 v232, v4, v5
	v_cvt_pk_bf16_f32 v233, v6, v7
	v_cvt_pk_bf16_f32 v234, v0, v1
	v_cvt_pk_bf16_f32 v235, v2, v3
	v_mov_b32_e32 v236, v228
	v_mov_b32_e32 v237, v229
	v_mov_b32_e32 v238, v230
	v_mov_b32_e32 v239, v231
	v_mov_b32_dpp v228, v232 row_ror:8 row_mask:0xf bank_mask:0xc
	v_mov_b32_dpp v229, v233 row_ror:8 row_mask:0xf bank_mask:0xc
	v_mov_b32_dpp v230, v234 row_ror:8 row_mask:0xf bank_mask:0xc
	v_mov_b32_dpp v231, v235 row_ror:8 row_mask:0xf bank_mask:0xc
	v_mov_b32_dpp v232, v236 row_ror:8 row_mask:0xf bank_mask:0x3
	v_mov_b32_dpp v233, v237 row_ror:8 row_mask:0xf bank_mask:0x3
	v_mov_b32_dpp v234, v238 row_ror:8 row_mask:0xf bank_mask:0x3
	v_mov_b32_dpp v235, v239 row_ror:8 row_mask:0xf bank_mask:0x3
	s_add_u32 s100, s100, 0x20000
	s_addc_u32 s101, s101, 0
	global_store_dwordx4 v240, v[228:231], s[100:101]
	s_add_u32 s100, s100, 0x20000
	s_addc_u32 s101, s101, 0
	global_store_dwordx4 v240, v[232:235], s[100:101]
	s_and_b64 vcc, exec, s[2:3]
	s_mov_b32 s47, s12
	s_mov_b32 s20, s14
	s_mov_b64 s[24:25], s[18:19]
	s_mov_b64 s[22:23], s[16:17]
	s_cbranch_vccz .LBB0_1561
	s_waitcnt vmcnt(0)
	s_cmpk_gt_u32 s28, 0xff
	s_cbranch_scc1 .LBB0_1568
	s_barrier

	.amdhsa_kernel _Z6k_mega6Params
		.amdhsa_group_segment_fixed_size 0
		.amdhsa_private_segment_fixed_size 0
		.amdhsa_kernarg_size 432
		.amdhsa_user_sgpr_count 2
		.amdhsa_user_sgpr_dispatch_ptr 0
		.amdhsa_user_sgpr_queue_ptr 0
		.amdhsa_user_sgpr_kernarg_segment_ptr 1
		.amdhsa_user_sgpr_dispatch_id 0
		.amdhsa_user_sgpr_kernarg_preload_length 0
		.amdhsa_user_sgpr_kernarg_preload_offset 0
		.amdhsa_user_sgpr_private_segment_size 0
		.amdhsa_uses_dynamic_stack 0
		.amdhsa_enable_private_segment 0
		.amdhsa_system_sgpr_workgroup_id_x 1
		.amdhsa_system_sgpr_workgroup_id_y 0
		.amdhsa_system_sgpr_workgroup_id_z 0
		.amdhsa_system_sgpr_workgroup_info 0
		.amdhsa_system_vgpr_workitem_id 2
		.amdhsa_next_free_vgpr 256
		.amdhsa_next_free_sgpr 102
		.amdhsa_accum_offset 256
		.amdhsa_reserve_vcc 1
		.amdhsa_float_round_mode_32 0
		.amdhsa_float_round_mode_16_64 0
		.amdhsa_float_denorm_mode_32 3
		.amdhsa_float_denorm_mode_16_64 3
		.amdhsa_dx10_clamp 1
		.amdhsa_ieee_mode 1
		.amdhsa_fp16_overflow 0
		.amdhsa_tg_split 0
		.amdhsa_exception_fp_ieee_invalid_op 0
		.amdhsa_exception_fp_denorm_src 0
		.amdhsa_exception_fp_ieee_div_zero 0
		.amdhsa_exception_fp_ieee_overflow 0
		.amdhsa_exception_fp_ieee_underflow 0
		.amdhsa_exception_fp_ieee_inexact 0
		.amdhsa_exception_int_div_zero 0
	.end_amdhsa_kernel

amdhsa.kernels:
  - .agpr_count:     0
    .args:
      - .offset:         0
        .size:           176
        .value_kind:     by_value
      - .offset:         176
        .size:           4
        .value_kind:     hidden_block_count_x
      - .offset:         180
        .size:           4
        .value_kind:     hidden_block_count_y
      - .offset:         184
        .size:           4
        .value_kind:     hidden_block_count_z
      - .offset:         188
        .size:           2
        .value_kind:     hidden_group_size_x
      - .offset:         190
        .size:           2
        .value_kind:     hidden_group_size_y
      - .offset:         192
        .size:           2
        .value_kind:     hidden_group_size_z
      - .offset:         194
        .size:           2
        .value_kind:     hidden_remainder_x
      - .offset:         196
        .size:           2
        .value_kind:     hidden_remainder_y
      - .offset:         198
        .size:           2
        .value_kind:     hidden_remainder_z
      - .offset:         216
        .size:           8
        .value_kind:     hidden_global_offset_x
      - .offset:         224
        .size:           8
        .value_kind:     hidden_global_offset_y
      - .offset:         232
        .size:           8
        .value_kind:     hidden_global_offset_z
      - .offset:         240
        .size:           2
        .value_kind:     hidden_grid_dims
      - .offset:         264
        .size:           8
        .value_kind:     hidden_multigrid_sync_arg
      - .offset:         296
        .size:           4
        .value_kind:     hidden_dynamic_lds_size
    .group_segment_fixed_size: 0
    .kernarg_segment_align: 8
    .kernarg_segment_size: 432
    .language:       OpenCL C
    .language_version:
      - 2
      - 0
    .max_flat_workgroup_size: 512
    .name:           _Z6k_mega6Params
    .private_segment_fixed_size: 0
    .sgpr_count:     108
    .sgpr_spill_count: 159
    .symbol:         _Z6k_mega6Params.kd
    .uniform_work_group_size: 1
    .uses_dynamic_stack: false
    .vgpr_count:     256
    .vgpr_spill_count: 0
    .wavefront_size: 64
